# v32 plus NA bias LDS reads hoisted above the QK MFMA pair (counted lgkmcnt)
# speedup vs baseline: 1.0007x; 1.0007x over previous
; #define LAS __attribute__((address_space(3)))
; #define MFMA32(a, b, c) __builtin_amdgcn_mfma_f32_16x16x32_bf16((a), (b), (c), 0, 0, 0)
; DI void na_phase(LAS unsigned char* lds, const Args& A, const bf16* proj, bf16* nao, int T, int nB, unsigned* counter, int tid_in) {
;     ...
;             for (int rr = 0; rr < 4; ++rr) { const int kr = rs + 4 * kh + rr, sl = kr & 7;
; #pragma unroll
;                 for (int ct = 0; ct < 2; ++ct) { const int cm = cs0 + 16 * ct + l15; f32x4 acc = (f32x4){0.f, 0.f, 0.f, 0.f};
; #pragma unroll
;                     for (int ks = 0; ks < 2; ++ks) { const bf16x8 kf = *(const LAS bf16x8*)(lds + NA_K + sl * 8192 + cm * 128 + (((4 * ks + g) ^ ((cm >> 1) & 7)) * 16)); acc = MFMA32(kf, qf[ks], acc); }
; #pragma unroll
;                     for (int e = 0; e < 4; ++e) { const int cc = cs0 + 16 * ct + 4 * g + e; const bool valid = (cc >= csq) && (cc < csq + 16);
;                         const int bi = (kr - r + 7) * 31 + min(max(cc - cq + 15, 0), 30);
;                         const float sv = valid ? acc[e] + BI[bi] : -INFINITY; acc[e] = sv; mx = fmaxf(mx, sv); }
.LBB0_337:
	v_add_u32_e32 v31, s38, v71
	v_lshlrev_b32_e32 v24, 13, v31
	v_and_b32_e32 v28, 0xe000, v24
	v_add_u32_e32 v30, 0, v28
	v_add_u32_e32 v29, v30, v91
	v_add_u32_e32 v24, v29, v92
	ds_read_b128 v[24:27], v24
	v_add_u32_e32 v29, v29, v93
	ds_read_b128 v[58:61], v29
	s_add_i32 s0, s19, s38
	v_add_u32_e32 v29, s0, v57
	v_mul_lo_u32 v29, v29, s88
	v_add_u32_e32 v38, s87, v29
	v_add_u32_e32 v29, 0xfffff080, v38
	v_mov_b32_e32 v63, 0xff800000
	v_lshl_add_u32 v252, v94, 2, v29
	ds_read_b32 v252, v252 offset:868
	v_lshl_add_u32 v253, v95, 2, v29
	ds_read_b32 v253, v253 offset:868
	v_lshl_add_u32 v254, v96, 2, v29
	ds_read_b32 v254, v254 offset:868
	v_lshl_add_u32 v255, v97, 2, v29
	ds_read_b32 v255, v255 offset:868
	s_waitcnt lgkmcnt(5)
	v_mfma_f32_16x16x32_bf16 v[24:27], v[24:27], v[20:23], 0
	s_waitcnt lgkmcnt(4)
	v_mfma_f32_16x16x32_bf16 v[24:27], v[58:61], v[16:19], v[24:27]
	v_mov_b32_e32 v59, 0xff800000
	s_waitcnt lgkmcnt(0)
	s_nop 5
	s_and_saveexec_b64 s[0:1], s[14:15]
	v_add_f32_e32 v63, v24, v252
	s_or_b64 exec, exec, s[0:1]
	s_and_saveexec_b64 s[0:1], s[16:17]
	v_add_f32_e32 v59, v25, v253
	s_or_b64 exec, exec, s[0:1]
	v_mov_b32_e32 v56, 0xff800000
	v_mov_b32_e32 v62, 0xff800000
	s_and_saveexec_b64 s[0:1], s[48:49]
	v_add_f32_e32 v62, v26, v254
	s_or_b64 exec, exec, s[0:1]
	s_and_saveexec_b64 s[0:1], s[50:51]
	v_add_f32_e32 v56, v27, v255
	s_or_b64 exec, exec, s[0:1]
	v_add_u32_e32 v30, v30, v98
	v_add_u32_e32 v24, v30, v92
	ds_read_b128 v[24:27], v24
	v_add_u32_e32 v30, v30, v93
	ds_read_b128 v[64:67], v30
	v_mov_b32_e32 v39, 0xff800000
	v_lshl_add_u32 v252, v99, 2, v29
	ds_read_b32 v252, v252 offset:868
	v_lshl_add_u32 v253, v100, 2, v29
	ds_read_b32 v253, v253 offset:868
	v_lshl_add_u32 v254, v101, 2, v29
	ds_read_b32 v254, v254 offset:868
	v_lshl_add_u32 v255, v102, 2, v29
	ds_read_b32 v255, v255 offset:868
	s_waitcnt lgkmcnt(5)
	v_mfma_f32_16x16x32_bf16 v[24:27], v[24:27], v[20:23], 0
	s_waitcnt lgkmcnt(4)
	v_mfma_f32_16x16x32_bf16 v[24:27], v[64:67], v[16:19], v[24:27]
	v_mov_b32_e32 v65, 0xff800000
	s_waitcnt lgkmcnt(0)
	s_nop 5
	s_and_saveexec_b64 s[0:1], s[52:53]
	v_add_f32_e32 v65, v24, v252
	s_or_b64 exec, exec, s[0:1]
	s_and_saveexec_b64 s[0:1], s[56:57]
	v_add_f32_e32 v39, v25, v253
	s_or_b64 exec, exec, s[0:1]
	v_mov_b32_e32 v54, 0xff800000
	v_mov_b32_e32 v55, 0xff800000
	s_and_saveexec_b64 s[0:1], s[76:77]
	v_add_f32_e32 v55, v26, v254
	s_or_b64 exec, exec, s[0:1]
	s_and_saveexec_b64 s[0:1], s[66:67]
	v_add_f32_e32 v54, v27, v255
	s_or_b64 exec, exec, s[0:1]
	v_lshl_add_u32 v24, v31, 13, v212
	v_and_b32_e32 v29, 0xe000, v24
	v_add_u32_e32 v66, 0, v29
	v_add_u32_e32 v30, v66, v91
	v_add_u32_e32 v24, v30, v92
	ds_read_b128 v[24:27], v24
	v_add_u32_e32 v30, v30, v93
	ds_read_b128 v[104:107], v30
	v_add_u32_e32 v30, 0xfffff0fc, v38
	v_mov_b32_e32 v58, 0xff800000
	v_mov_b32_e32 v60, 0xff800000
	v_lshl_add_u32 v252, v94, 2, v30
	ds_read_b32 v252, v252 offset:868
	v_lshl_add_u32 v253, v95, 2, v30
	ds_read_b32 v253, v253 offset:868
	v_lshl_add_u32 v254, v96, 2, v30
	ds_read_b32 v254, v254 offset:868
	v_lshl_add_u32 v255, v97, 2, v30
	ds_read_b32 v255, v255 offset:868
	s_waitcnt lgkmcnt(5)
	v_mfma_f32_16x16x32_bf16 v[24:27], v[24:27], v[20:23], 0
	s_waitcnt lgkmcnt(4)
	v_mfma_f32_16x16x32_bf16 v[24:27], v[104:107], v[16:19], v[24:27]
	s_waitcnt lgkmcnt(0)
	s_nop 5
	s_and_saveexec_b64 s[0:1], s[14:15]
	v_add_f32_e32 v60, v24, v252
	s_or_b64 exec, exec, s[0:1]
	s_and_saveexec_b64 s[0:1], s[16:17]
	v_add_f32_e32 v58, v25, v253
	s_or_b64 exec, exec, s[0:1]
	v_mov_b32_e32 v61, 0xff800000
	v_mov_b32_e32 v64, 0xff800000
	s_and_saveexec_b64 s[0:1], s[48:49]
	v_add_f32_e32 v64, v26, v254
	s_or_b64 exec, exec, s[0:1]
	s_and_saveexec_b64 s[0:1], s[50:51]
	v_add_f32_e32 v61, v27, v255
	s_or_b64 exec, exec, s[0:1]
	v_add_u32_e32 v66, v66, v98
	v_add_u32_e32 v24, v66, v92
	ds_read_b128 v[24:27], v24
	v_add_u32_e32 v66, v66, v93
	ds_read_b128 v[104:107], v66
	v_mov_b32_e32 v66, 0xff800000
	v_mov_b32_e32 v67, 0xff800000
	v_lshl_add_u32 v252, v99, 2, v30
	ds_read_b32 v252, v252 offset:868
	v_lshl_add_u32 v253, v100, 2, v30
	ds_read_b32 v253, v253 offset:868
	v_lshl_add_u32 v254, v101, 2, v30
	ds_read_b32 v254, v254 offset:868
	v_lshl_add_u32 v255, v102, 2, v30
	ds_read_b32 v255, v255 offset:868
	s_waitcnt lgkmcnt(5)
	v_mfma_f32_16x16x32_bf16 v[24:27], v[24:27], v[20:23], 0
	s_waitcnt lgkmcnt(4)
	v_mfma_f32_16x16x32_bf16 v[24:27], v[104:107], v[16:19], v[24:27]
	s_waitcnt lgkmcnt(0)
	s_nop 5
	s_and_saveexec_b64 s[0:1], s[52:53]
	v_add_f32_e32 v67, v24, v252
	s_or_b64 exec, exec, s[0:1]
	s_and_saveexec_b64 s[0:1], s[56:57]
	v_add_f32_e32 v66, v25, v253
	s_or_b64 exec, exec, s[0:1]
	v_mov_b32_e32 v104, 0xff800000
	v_mov_b32_e32 v105, 0xff800000
	s_and_saveexec_b64 s[0:1], s[76:77]
	v_add_f32_e32 v105, v26, v254
	s_or_b64 exec, exec, s[0:1]
	s_and_saveexec_b64 s[0:1], s[66:67]
	v_add_f32_e32 v104, v27, v255
	s_or_b64 exec, exec, s[0:1]
	v_lshl_add_u32 v24, v31, 13, v213
	v_and_b32_e32 v30, 0xe000, v24
	v_add_u32_e32 v110, 0, v30
	v_add_u32_e32 v106, v110, v91
	v_add_u32_e32 v24, v106, v92
	ds_read_b128 v[24:27], v24
	v_add_u32_e32 v106, v106, v93
	ds_read_b128 v[106:109], v106
	v_add_u32_e32 v114, 0xfffff178, v38
	v_lshl_add_u32 v252, v94, 2, v114
	ds_read_b32 v252, v252 offset:868
	v_lshl_add_u32 v253, v95, 2, v114
	ds_read_b32 v253, v253 offset:868
	v_lshl_add_u32 v254, v96, 2, v114
	ds_read_b32 v254, v254 offset:868
	v_lshl_add_u32 v255, v97, 2, v114
	ds_read_b32 v255, v255 offset:868
	s_waitcnt lgkmcnt(5)
	v_mfma_f32_16x16x32_bf16 v[24:27], v[24:27], v[20:23], 0
	s_waitcnt lgkmcnt(4)
; #define LAS __attribute__((address_space(3)))
; #define MFMA32(a, b, c) __builtin_amdgcn_mfma_f32_16x16x32_bf16((a), (b), (c), 0, 0, 0)
; DI void na_phase(LAS unsigned char* lds, const Args& A, const bf16* proj, bf16* nao, int T, int nB, unsigned* counter, int tid_in) {
;     ...
;             for (int rr = 0; rr < 4; ++rr) { const int kr = rs + 4 * kh + rr, sl = kr & 7;
; #pragma unroll
;                 for (int ct = 0; ct < 2; ++ct) { const int cm = cs0 + 16 * ct + l15; f32x4 acc = (f32x4){0.f, 0.f, 0.f, 0.f};
; #pragma unroll
;                     for (int ks = 0; ks < 2; ++ks) { const bf16x8 kf = *(const LAS bf16x8*)(lds + NA_K + sl * 8192 + cm * 128 + (((4 * ks + g) ^ ((cm >> 1) & 7)) * 16)); acc = MFMA32(kf, qf[ks], acc); }
; #pragma unroll
;                     for (int e = 0; e < 4; ++e) { const int cc = cs0 + 16 * ct + 4 * g + e; const bool valid = (cc >= csq) && (cc < csq + 16);
;                         const int bi = (kr - r + 7) * 31 + min(max(cc - cq + 15, 0), 30);
;                         const float sv = valid ? acc[e] + BI[bi] : -INFINITY; acc[e] = sv; mx = fmaxf(mx, sv); }
;                     sT[rr][ct] = acc; } }
;             mx = fmaxf(mx, __shfl_xor(mx, 16)); mx = fmaxf(mx, __shfl_xor(mx, 32));
	v_mfma_f32_16x16x32_bf16 v[24:27], v[106:109], v[16:19], v[24:27]
	v_mov_b32_e32 v106, 0xff800000
	v_mov_b32_e32 v107, 0xff800000
	s_waitcnt lgkmcnt(0)
	s_nop 5
	s_and_saveexec_b64 s[0:1], s[14:15]
	v_add_f32_e32 v107, v24, v252
	s_or_b64 exec, exec, s[0:1]
	s_and_saveexec_b64 s[0:1], s[16:17]
	v_add_f32_e32 v106, v25, v253
	s_or_b64 exec, exec, s[0:1]
	v_mov_b32_e32 v108, 0xff800000
	v_mov_b32_e32 v109, 0xff800000
	s_and_saveexec_b64 s[0:1], s[48:49]
	v_add_f32_e32 v109, v26, v254
	s_or_b64 exec, exec, s[0:1]
	s_and_saveexec_b64 s[0:1], s[50:51]
	v_add_f32_e32 v108, v27, v255
	s_or_b64 exec, exec, s[0:1]
	v_add_u32_e32 v110, v110, v98
	v_add_u32_e32 v24, v110, v92
	ds_read_b128 v[24:27], v24
	v_add_u32_e32 v110, v110, v93
	ds_read_b128 v[110:113], v110
	v_lshl_add_u32 v252, v99, 2, v114
	ds_read_b32 v252, v252 offset:868
	v_lshl_add_u32 v253, v100, 2, v114
	ds_read_b32 v253, v253 offset:868
	v_lshl_add_u32 v254, v101, 2, v114
	ds_read_b32 v254, v254 offset:868
	v_lshl_add_u32 v255, v102, 2, v114
	ds_read_b32 v255, v255 offset:868
	s_waitcnt lgkmcnt(5)
	v_mfma_f32_16x16x32_bf16 v[24:27], v[24:27], v[20:23], 0
	s_waitcnt lgkmcnt(4)
	v_mfma_f32_16x16x32_bf16 v[24:27], v[110:113], v[16:19], v[24:27]
	v_mov_b32_e32 v110, 0xff800000
	v_mov_b32_e32 v111, 0xff800000
	s_waitcnt lgkmcnt(0)
	s_nop 5
	s_and_saveexec_b64 s[0:1], s[52:53]
	v_add_f32_e32 v111, v24, v252
	s_or_b64 exec, exec, s[0:1]
	s_and_saveexec_b64 s[0:1], s[56:57]
	v_add_f32_e32 v110, v25, v253
	s_or_b64 exec, exec, s[0:1]
	v_mov_b32_e32 v112, 0xff800000
	v_mov_b32_e32 v113, 0xff800000
	s_and_saveexec_b64 s[0:1], s[76:77]
	v_add_f32_e32 v113, v26, v254
	s_or_b64 exec, exec, s[0:1]
	s_and_saveexec_b64 s[0:1], s[66:67]
	v_add_f32_e32 v112, v27, v255
	s_or_b64 exec, exec, s[0:1]
	v_lshl_add_u32 v24, v31, 13, v214
	v_and_b32_e32 v31, 0xe000, v24
	v_add_u32_e32 v116, 0, v31
	v_add_u32_e32 v114, v116, v91
	v_add_u32_e32 v24, v114, v92
	ds_read_b128 v[24:27], v24
	v_add_u32_e32 v114, v114, v93
	ds_read_b128 v[118:121], v114
	v_add_u32_e32 v38, 0xfffff1f4, v38
	v_mov_b32_e32 v114, 0xff800000
	v_mov_b32_e32 v115, 0xff800000
	v_lshl_add_u32 v252, v94, 2, v38
	ds_read_b32 v252, v252 offset:868
	v_lshl_add_u32 v253, v95, 2, v38
	ds_read_b32 v253, v253 offset:868
	s_waitcnt lgkmcnt(3)
	v_mfma_f32_16x16x32_bf16 v[24:27], v[24:27], v[20:23], 0
	s_waitcnt lgkmcnt(2)
	v_mfma_f32_16x16x32_bf16 v[24:27], v[118:121], v[16:19], v[24:27]
	s_waitcnt lgkmcnt(0)
	s_nop 5
	s_and_saveexec_b64 s[0:1], s[14:15]
	v_add_f32_e32 v115, v24, v252
	s_or_b64 exec, exec, s[0:1]
	s_and_saveexec_b64 s[0:1], s[16:17]
	v_add_f32_e32 v114, v25, v253
	s_or_b64 exec, exec, s[0:1]
	s_nop 1
	v_mov_b32_e32 v24, 0xff800000
	v_mov_b32_e32 v25, 0xff800000
	v_lshl_add_u32 v252, v96, 2, v38
	ds_read_b32 v252, v252 offset:868
	v_lshl_add_u32 v253, v97, 2, v38
	ds_read_b32 v253, v253 offset:868
	s_waitcnt lgkmcnt(0)
	s_nop 2
	s_and_saveexec_b64 s[0:1], s[48:49]
	v_add_f32_e32 v25, v26, v252
	s_or_b64 exec, exec, s[0:1]
	s_and_saveexec_b64 s[0:1], s[50:51]
	v_add_f32_e32 v24, v27, v253
	s_or_b64 exec, exec, s[0:1]
	v_add_u32_e32 v26, v116, v98
	v_add_u32_e32 v27, v26, v92
	ds_read_b128 v[116:119], v27
	v_add_u32_e32 v26, v26, v93
	s_waitcnt lgkmcnt(0)
	v_mfma_f32_16x16x32_bf16 v[20:23], v[116:119], v[20:23], 0
	ds_read_b128 v[116:119], v26
	s_waitcnt lgkmcnt(0)
	v_mfma_f32_16x16x32_bf16 v[16:19], v[116:119], v[16:19], v[20:23]
	s_nop 4
	v_mov_b32_e32 v20, 0xff800000
	v_mov_b32_e32 v21, 0xff800000
	v_lshl_add_u32 v252, v99, 2, v38
	ds_read_b32 v252, v252 offset:868
	v_lshl_add_u32 v253, v100, 2, v38
	ds_read_b32 v253, v253 offset:868
	v_lshl_add_u32 v254, v101, 2, v38
	ds_read_b32 v254, v254 offset:868
	v_lshl_add_u32 v255, v102, 2, v38
	ds_read_b32 v255, v255 offset:868
	s_waitcnt lgkmcnt(0)
	s_and_saveexec_b64 s[0:1], s[52:53]
	v_add_f32_e32 v21, v16, v252
	s_or_b64 exec, exec, s[0:1]
	s_and_saveexec_b64 s[0:1], s[56:57]
	v_add_f32_e32 v20, v17, v253
	s_or_b64 exec, exec, s[0:1]
	v_mov_b32_e32 v16, 0xff800000
	v_mov_b32_e32 v17, 0xff800000
	s_and_saveexec_b64 s[0:1], s[76:77]
	v_add_f32_e32 v17, v18, v254
	s_or_b64 exec, exec, s[0:1]
	s_and_saveexec_b64 s[0:1], s[66:67]
	v_add_f32_e32 v16, v19, v255
	s_or_b64 exec, exec, s[0:1]
	v_max3_f32 v18, v63, s89, v59
	v_max3_f32 v18, v18, v62, v56
	v_max3_f32 v18, v18, v65, v39
	v_max3_f32 v18, v18, v55, v54
	v_max3_f32 v18, v18, v60, v58
	v_max3_f32 v18, v18, v64, v61
	v_max3_f32 v18, v18, v67, v66
	v_max3_f32 v18, v18, v105, v104
	v_max3_f32 v18, v18, v107, v106
	v_max3_f32 v18, v18, v109, v108
	v_max3_f32 v18, v18, v111, v110
	v_max3_f32 v18, v18, v113, v112
	v_max3_f32 v18, v18, v115, v114
	v_max3_f32 v18, v18, v25, v24
	v_max3_f32 v18, v18, v21, v20
	v_max3_f32 v18, v18, v17, v16
	ds_bpermute_b32 v19, v72, v18
	s_waitcnt lgkmcnt(0)
	v_max_f32_e32 v19, v19, v19
	v_max_f32_e32 v18, v18, v19
	ds_bpermute_b32 v19, v73, v18
	s_waitcnt lgkmcnt(0)
; #define LAS __attribute__((address_space(3)))
; DI unsigned pk2(float lo, float hi) { f32x2 v = {lo, hi}; bf16v2 b = __builtin_convertvector(v, bf16v2); return __builtin_bit_cast(unsigned, b); }
; DI void na_phase(LAS unsigned char* lds, const Args& A, const bf16* proj, bf16* nao, int T, int nB, unsigned* counter, int tid_in) {
;     ...
;             mx = fmaxf(mx, __shfl_xor(mx, 16)); mx = fmaxf(mx, __shfl_xor(mx, 32));
;             float lsum = 0.f;
; #pragma unroll
;             for (int rr = 0; rr < 4; ++rr)
; #pragma unroll
;                 for (int ct = 0; ct < 2; ++ct)
; #pragma unroll
;                     for (int e = 0; e < 4; ++e) { const float p = __expf(sT[rr][ct][e] - mx); sT[rr][ct][e] = p; lsum += p; }
;             lsum += __shfl_xor(lsum, 16); lsum += __shfl_xor(lsum, 32);
;             f32x4 O[4];
; #pragma unroll
;             for (int mt = 0; mt < 4; ++mt) O[mt] = (f32x4){0.f, 0.f, 0.f, 0.f};
; #pragma unroll
;             for (int rr = 0; rr < 4; ++rr) { const int sl = (rs + 4 * kh + rr) & 7;
;                 const u32x4 pw = (u32x4){pk2(sT[rr][0][0], sT[rr][0][1]), pk2(sT[rr][0][2], sT[rr][0][3]), pk2(sT[rr][1][0], sT[rr][1][1]), pk2(sT[rr][1][2], sT[rr][1][3])};
;                 const bf16x8 pb = __builtin_bit_cast(bf16x8, pw);
; #pragma unroll
;                 for (int mt = 0; mt < 4; ++mt) { const int dd = 16 * mt + l15, sw = 2 * ((dd >> 1) & 7);
;                     const LAS unsigned char* vb = lds + NA_V + sl * 8192 + dd * 128;
;                     const u32x2 lo = *(const LAS u32x2*)(vb + ((((cs0 >> 2) + g) ^ sw) * 8)), hi = *(const LAS u32x2*)(vb + ((((cs0 >> 2) + 4 + g) ^ sw) * 8));
	v_max_f32_e32 v19, v19, v19
	v_max_f32_e32 v38, v18, v19
	v_sub_f32_e32 v39, v39, v38
	v_mul_f32_e32 v39, 0x3fb8aa3b, v39
	v_sub_f32_e32 v26, v56, v38
	v_exp_f32_e32 v56, v39
	v_sub_f32_e32 v39, v55, v38
	v_mul_f32_e32 v39, 0x3fb8aa3b, v39
	v_exp_f32_e32 v55, v39
	v_sub_f32_e32 v39, v54, v38
	v_mul_f32_e32 v39, 0x3fb8aa3b, v39
	v_sub_f32_e32 v22, v59, v38
	v_exp_f32_e32 v59, v39
	v_sub_f32_e32 v39, v60, v38
	v_mul_f32_e32 v39, 0x3fb8aa3b, v39
	v_exp_f32_e32 v116, v39
	v_sub_f32_e32 v39, v58, v38
	v_mul_f32_e32 v39, 0x3fb8aa3b, v39
	v_exp_f32_e32 v117, v39
	v_sub_f32_e32 v39, v64, v38
	v_mul_f32_e32 v39, 0x3fb8aa3b, v39
	v_exp_f32_e32 v118, v39
	v_sub_f32_e32 v39, v61, v38
	v_mul_f32_e32 v39, 0x3fb8aa3b, v39
	v_exp_f32_e32 v119, v39
	v_sub_f32_e32 v39, v67, v38
	v_sub_f32_e32 v18, v63, v38
	v_mul_f32_e32 v39, 0x3fb8aa3b, v39
	v_mul_f32_e32 v18, 0x3fb8aa3b, v18
	v_exp_f32_e32 v67, v39
	v_sub_f32_e32 v39, v66, v38
	v_exp_f32_e32 v18, v18
	v_mul_f32_e32 v22, 0x3fb8aa3b, v22
	v_sub_f32_e32 v23, v62, v38
	v_mul_f32_e32 v39, 0x3fb8aa3b, v39
	v_exp_f32_e32 v22, v22
	v_mul_f32_e32 v23, 0x3fb8aa3b, v23
	v_exp_f32_e32 v66, v39
	v_sub_f32_e32 v39, v105, v38
	v_exp_f32_e32 v23, v23
	v_mul_f32_e32 v26, 0x3fb8aa3b, v26
	v_sub_f32_e32 v27, v65, v38
	v_mul_f32_e32 v39, 0x3fb8aa3b, v39
	v_exp_f32_e32 v26, v26
	v_mul_f32_e32 v27, 0x3fb8aa3b, v27
	v_exp_f32_e32 v120, v39
	v_sub_f32_e32 v39, v104, v38
	v_add_f32_e32 v19, 0, v18
	v_exp_f32_e32 v27, v27
	v_mul_f32_e32 v39, 0x3fb8aa3b, v39
	v_add_f32_e32 v19, v22, v19
	v_exp_f32_e32 v121, v39
	v_sub_f32_e32 v39, v107, v38
	v_add_f32_e32 v19, v23, v19
	v_mul_f32_e32 v39, 0x3fb8aa3b, v39
	v_add_f32_e32 v19, v26, v19
	v_exp_f32_e32 v122, v39
	v_sub_f32_e32 v39, v106, v38
	v_add_f32_e32 v19, v27, v19
	v_mul_f32_e32 v39, 0x3fb8aa3b, v39
	v_add_f32_e32 v19, v56, v19
	v_exp_f32_e32 v123, v39
	v_sub_f32_e32 v39, v109, v38
	v_add_f32_e32 v19, v55, v19
	v_mul_f32_e32 v39, 0x3fb8aa3b, v39
	v_add_f32_e32 v19, v59, v19
	v_exp_f32_e32 v124, v39
	v_sub_f32_e32 v39, v108, v38
	v_add_f32_e32 v19, v116, v19
	v_mul_f32_e32 v39, 0x3fb8aa3b, v39
	v_add_f32_e32 v19, v117, v19
	v_exp_f32_e32 v125, v39
	v_sub_f32_e32 v39, v111, v38
	v_add_f32_e32 v19, v118, v19
	v_mul_f32_e32 v39, 0x3fb8aa3b, v39
	v_add_f32_e32 v19, v119, v19
	v_exp_f32_e32 v126, v39
	v_sub_f32_e32 v39, v110, v38
	v_add_f32_e32 v19, v67, v19
	v_mul_f32_e32 v39, 0x3fb8aa3b, v39
	v_add_f32_e32 v19, v66, v19
	v_exp_f32_e32 v127, v39
	v_sub_f32_e32 v39, v113, v38
	v_add_f32_e32 v19, v120, v19
	v_mul_f32_e32 v39, 0x3fb8aa3b, v39
	v_add_f32_e32 v19, v121, v19
	v_exp_f32_e32 v128, v39
	v_sub_f32_e32 v39, v112, v38
	v_add_f32_e32 v19, v122, v19
	v_mul_f32_e32 v39, 0x3fb8aa3b, v39
	v_add_f32_e32 v19, v123, v19
	v_exp_f32_e32 v129, v39
	v_sub_f32_e32 v39, v115, v38
	v_add_f32_e32 v19, v124, v19
	v_mul_f32_e32 v39, 0x3fb8aa3b, v39
	v_add_f32_e32 v19, v125, v19
	v_exp_f32_e32 v130, v39
	v_sub_f32_e32 v39, v114, v38
	v_add_f32_e32 v19, v126, v19
	v_mul_f32_e32 v39, 0x3fb8aa3b, v39
	v_sub_f32_e32 v25, v25, v38
	v_add_f32_e32 v19, v127, v19
	v_exp_f32_e32 v131, v39
	v_mul_f32_e32 v25, 0x3fb8aa3b, v25
	v_sub_f32_e32 v24, v24, v38
	v_add_f32_e32 v19, v128, v19
	v_exp_f32_e32 v132, v25
	v_mul_f32_e32 v24, 0x3fb8aa3b, v24
	v_sub_f32_e32 v21, v21, v38
	v_add_f32_e32 v19, v129, v19
	v_exp_f32_e32 v133, v24
	v_mul_f32_e32 v21, 0x3fb8aa3b, v21
	v_sub_f32_e32 v20, v20, v38
	v_add_f32_e32 v19, v130, v19
	v_exp_f32_e32 v134, v21
	v_mul_f32_e32 v20, 0x3fb8aa3b, v20
	v_sub_f32_e32 v17, v17, v38
	v_add_f32_e32 v19, v131, v19
	v_exp_f32_e32 v135, v20
	v_mul_f32_e32 v17, 0x3fb8aa3b, v17
	v_sub_f32_e32 v16, v16, v38
	v_add_f32_e32 v19, v132, v19
	v_exp_f32_e32 v136, v17
	v_mul_f32_e32 v16, 0x3fb8aa3b, v16
	v_add_f32_e32 v19, v133, v19
	v_exp_f32_e32 v137, v16
	v_add_f32_e32 v19, v134, v19
	v_add_f32_e32 v19, v135, v19
	v_add_f32_e32 v17, v136, v19
	v_add_f32_e32 v16, v137, v17
	ds_bpermute_b32 v17, v72, v16
	v_add_u32_e32 v24, v74, v28
	v_cvt_pk_bf16_f32 v19, v55, v59
	v_add_u32_e32 v28, v24, v75
	v_add_u32_e32 v55, v24, v76
	s_waitcnt lgkmcnt(0)
	v_add_f32_e32 v39, v16, v17
	v_cvt_pk_bf16_f32 v16, v18, v22
	v_cvt_pk_bf16_f32 v17, v23, v26
	v_cvt_pk_bf16_f32 v18, v27, v56
	ds_read2st64_b64 v[20:23], v28 offset1:4
	ds_read2st64_b64 v[24:27], v55 offset1:4
	ds_bpermute_b32 v54, v73, v39
	s_waitcnt lgkmcnt(2)
	v_mov_b32_e32 v58, v20
	s_waitcnt lgkmcnt(1)
; #define LAS __attribute__((address_space(3)))
; DI unsigned pk2(float lo, float hi) { f32x2 v = {lo, hi}; bf16v2 b = __builtin_convertvector(v, bf16v2); return __builtin_bit_cast(unsigned, b); }
; #define MFMA32(a, b, c) __builtin_amdgcn_mfma_f32_16x16x32_bf16((a), (b), (c), 0, 0, 0)
; DI void na_phase(LAS unsigned char* lds, const Args& A, const bf16* proj, bf16* nao, int T, int nB, unsigned* counter, int tid_in) {
;     ...
; #pragma unroll
;             for (int mt = 0; mt < 4; ++mt) O[mt] = (f32x4){0.f, 0.f, 0.f, 0.f};
; #pragma unroll
;             for (int rr = 0; rr < 4; ++rr) { const int sl = (rs + 4 * kh + rr) & 7;
;                 const u32x4 pw = (u32x4){pk2(sT[rr][0][0], sT[rr][0][1]), pk2(sT[rr][0][2], sT[rr][0][3]), pk2(sT[rr][1][0], sT[rr][1][1]), pk2(sT[rr][1][2], sT[rr][1][3])};
;                 const bf16x8 pb = __builtin_bit_cast(bf16x8, pw);
; #pragma unroll
;                 for (int mt = 0; mt < 4; ++mt) { const int dd = 16 * mt + l15, sw = 2 * ((dd >> 1) & 7);
;                     const LAS unsigned char* vb = lds + NA_V + sl * 8192 + dd * 128;
;                     const u32x2 lo = *(const LAS u32x2*)(vb + ((((cs0 >> 2) + g) ^ sw) * 8)), hi = *(const LAS u32x2*)(vb + ((((cs0 >> 2) + 4 + g) ^ sw) * 8));
;                     const u32x4 vv = (u32x4){lo.x, lo.y, hi.x, hi.y};
;                     O[mt] = MFMA32(__builtin_bit_cast(bf16x8, vv), pb, O[mt]); } }
;             LAS float* MG = (LAS float*)(lds + NA_MRG + qg * 4608) + lane;
;             if (kh == 1) { MG[0] = mx; MG[64] = lsum;
; #pragma unroll
;                 for (int mt = 0; mt < 4; ++mt)
; #pragma unroll
;                     for (int e = 0; e < 4; ++e) MG[(2 + mt * 4 + e) * 64] = O[mt][e]; }
	v_mov_b32_e32 v60, v24
	v_mov_b32_e32 v61, v25
	v_mov_b32_e32 v24, v22
	v_mov_b32_e32 v25, v23
	v_mov_b32_e32 v59, v21
	s_waitcnt lgkmcnt(0)
	v_add_f32_e32 v54, v39, v54
	v_mfma_f32_16x16x32_bf16 v[20:23], v[24:27], v[16:19], 0
	ds_read2st64_b64 v[24:27], v28 offset0:8 offset1:12
	ds_read2st64_b64 v[62:65], v55 offset0:8 offset1:12
	v_add_u32_e32 v28, v74, v29
	v_add_u32_e32 v29, v28, v75
	v_add_u32_e32 v28, v28, v76
	s_waitcnt lgkmcnt(1)
	v_mov_b32_e32 v104, v24
	v_mov_b32_e32 v105, v25
	s_waitcnt lgkmcnt(0)
	v_mov_b32_e32 v106, v62
	v_mov_b32_e32 v107, v63
	v_mov_b32_e32 v62, v26
	v_mov_b32_e32 v63, v27
	v_mfma_f32_16x16x32_bf16 v[58:61], v[58:61], v[16:19], 0
	ds_read2st64_b64 v[108:111], v28 offset1:4
	v_cvt_pk_bf16_f32 v24, v116, v117
	v_cvt_pk_bf16_f32 v25, v118, v119
	v_mfma_f32_16x16x32_bf16 v[104:107], v[104:107], v[16:19], 0
	v_cvt_pk_bf16_f32 v26, v67, v66
	s_waitcnt lgkmcnt(0)
	v_mov_b32_e32 v114, v108
	v_mov_b32_e32 v115, v109
	v_mfma_f32_16x16x32_bf16 v[16:19], v[62:65], v[16:19], 0
	ds_read2st64_b64 v[62:65], v29 offset1:4
	v_cvt_pk_bf16_f32 v27, v120, v121
	s_waitcnt lgkmcnt(0)
	v_mov_b32_e32 v108, v64
	v_mov_b32_e32 v109, v65
	v_mov_b32_e32 v112, v62
	v_mov_b32_e32 v113, v63
	v_mfma_f32_16x16x32_bf16 v[20:23], v[108:111], v[24:27], v[20:23]
	ds_read2st64_b64 v[62:65], v29 offset0:8 offset1:12
	ds_read2st64_b64 v[108:111], v28 offset0:8 offset1:12
	v_add_u32_e32 v28, v74, v30
	v_add_u32_e32 v29, v28, v75
	v_mfma_f32_16x16x32_bf16 v[58:61], v[112:115], v[24:27], v[58:61]
	v_add_u32_e32 v28, v28, v76
	s_waitcnt lgkmcnt(0)
	v_mov_b32_e32 v114, v108
	v_mov_b32_e32 v115, v109
	v_mov_b32_e32 v108, v64
	v_mov_b32_e32 v109, v65
	v_mov_b32_e32 v112, v62
	v_mov_b32_e32 v113, v63
	v_mfma_f32_16x16x32_bf16 v[16:19], v[108:111], v[24:27], v[16:19]
	ds_read2st64_b64 v[62:65], v29 offset1:4
	ds_read2st64_b64 v[108:111], v28 offset1:4
	v_mfma_f32_16x16x32_bf16 v[104:107], v[112:115], v[24:27], v[104:107]
	v_cvt_pk_bf16_f32 v24, v122, v123
	v_cvt_pk_bf16_f32 v25, v124, v125
	s_waitcnt lgkmcnt(0)
	v_mov_b32_e32 v114, v108
	v_mov_b32_e32 v115, v109
	v_mov_b32_e32 v108, v64
	v_mov_b32_e32 v109, v65
	v_cvt_pk_bf16_f32 v26, v126, v127
	v_cvt_pk_bf16_f32 v27, v128, v129
	v_mov_b32_e32 v112, v62
	v_mov_b32_e32 v113, v63
	v_mfma_f32_16x16x32_bf16 v[20:23], v[108:111], v[24:27], v[20:23]
	ds_read2st64_b64 v[62:65], v29 offset0:8 offset1:12
	ds_read2st64_b64 v[108:111], v28 offset0:8 offset1:12
	v_add_u32_e32 v28, v74, v31
	v_add_u32_e32 v55, v28, v75
	v_mfma_f32_16x16x32_bf16 v[58:61], v[112:115], v[24:27], v[58:61]
	s_waitcnt lgkmcnt(1)
	v_mov_b32_e32 v112, v62
	v_mov_b32_e32 v113, v63
	s_waitcnt lgkmcnt(0)
	v_mov_b32_e32 v114, v108
	v_mov_b32_e32 v115, v109
	v_mov_b32_e32 v108, v64
	v_mov_b32_e32 v109, v65
	v_add_u32_e32 v56, v28, v76
	v_mfma_f32_16x16x32_bf16 v[104:107], v[112:115], v[24:27], v[104:107]
	v_cvt_pk_bf16_f32 v62, v130, v131
	v_cvt_pk_bf16_f32 v63, v132, v133
	v_cvt_pk_bf16_f32 v64, v134, v135
	v_mfma_f32_16x16x32_bf16 v[16:19], v[108:111], v[24:27], v[16:19]
	ds_read2st64_b64 v[24:27], v55 offset1:4
	ds_read2st64_b64 v[108:111], v56 offset1:4
	v_cvt_pk_bf16_f32 v65, v136, v137
	s_waitcnt lgkmcnt(1)
	v_mov_b32_e32 v28, v24
	v_mov_b32_e32 v29, v25
	s_waitcnt lgkmcnt(0)
	v_mov_b32_e32 v30, v108
	v_mov_b32_e32 v31, v109
	v_mov_b32_e32 v108, v26
	v_mov_b32_e32 v109, v27
	v_mfma_f32_16x16x32_bf16 v[28:31], v[28:31], v[62:65], v[58:61]
	s_nop 0
	v_mfma_f32_16x16x32_bf16 v[24:27], v[108:111], v[62:65], v[20:23]
	s_nop 0
	ds_read2st64_b64 v[58:61], v55 offset0:8 offset1:12
	ds_read2st64_b64 v[108:111], v56 offset0:8 offset1:12
	s_waitcnt lgkmcnt(1)
	v_mov_b32_e32 v20, v58
	v_mov_b32_e32 v21, v59
	s_waitcnt lgkmcnt(0)
	v_mov_b32_e32 v22, v108
	v_mov_b32_e32 v23, v109
	v_mov_b32_e32 v108, v60
	v_mov_b32_e32 v109, v61
	v_mfma_f32_16x16x32_bf16 v[20:23], v[20:23], v[62:65], v[104:107]
	s_nop 0
	v_mfma_f32_16x16x32_bf16 v[16:19], v[108:111], v[62:65], v[16:19]
	s_and_saveexec_b64 s[0:1], s[42:43]
	s_cbranch_execz .LBB0_403
	ds_write2st64_b32 v103, v38, v54 offset1:1
	ds_write2st64_b32 v103, v28, v29 offset0:2 offset1:3
	ds_write2st64_b32 v103, v30, v31 offset0:4 offset1:5
	ds_write2st64_b32 v103, v24, v25 offset0:6 offset1:7
	ds_write2st64_b32 v103, v26, v27 offset0:8 offset1:9
	ds_write2st64_b32 v103, v20, v21 offset0:10 offset1:11
	ds_write2st64_b32 v103, v22, v23 offset0:12 offset1:13
	ds_write2st64_b32 v103, v16, v17 offset0:14 offset1:15
	ds_write2st64_b32 v103, v18, v19 offset0:16 offset1:17
